# scan: q/k chunk images stored with permuted channel order so one b128 fragment serves both P=kq^T and S^T q; four ds_read2_b64 per wave per chunk removed
# speedup vs baseline: 1.0095x; 1.0095x over previous
; __device__ __forceinline__ int opaque_tid() { int t = threadIdx.x; asm volatile("" : "+v"(t)); return t; }
; __device__ __forceinline__ void scan_phase(LAS unsigned char* lds, bf16* proj, int G, int bid) {
;     const int tid = opaque_tid(), lane = tid & 63, wave = tid >> 6, fr = lane & 15, fq = lane >> 4;
;     constexpr int KRS = 132;
;     constexpr int SET = 34304, O_KR = 0, O_QR = 8448, O_QE = 16896, O_KE = 21248, O_KD = 25600, O_DV = 33792, O_VT = 2 * SET, QST = 272;
;     const int st = tid >> 4, sc8 = tid & 15;
;     const int pdk = tid >> 2, ptq = tid & 3;
;     const bool stager = tid < 256;
;     ...
;     for (int chain = bid; chain < 256; chain += G) {
;         const int b = chain >> 4, h = (chain >> 1) & 7, dir = chain & 1;
;         const int kcol = 1024 + dir * 1024 + h * 128;
;         f32x4 S[8];
; #pragma unroll
;         for (int i = 0; i < 8; ++i) S[i] = (f32x4){0.f, 0.f, 0.f, 0.f};
;         u32x4 rk = (u32x4){0u, 0u, 0u, 0u}, rq = rk, rv = rk;
.LBB0_413:
	s_or_b64 exec, exec, s[0:1]
	v_readlane_b32 s0, v255, 33
	v_readlane_b32 s1, v255, 34
	s_xor_b64 s[0:1], s[0:1], -1
	v_writelane_b32 v255, s0, 46
	s_waitcnt lgkmcnt(0)
	s_barrier
	v_writelane_b32 v255, s1, 47
	s_nop 0
	v_readlane_b32 s0, v255, 39
	v_readlane_b32 s1, v255, 40
	s_and_b64 vcc, exec, s[0:1]
	s_mov_b64 s[0:1], -1
	s_cbranch_vccnz .LBB0_592
	v_readlane_b32 s4, v254, 43
	v_readlane_b32 s5, v254, 44
	s_and_b64 vcc, exec, s[4:5]
	s_cbranch_vccz .LBB0_496
	v_readlane_b32 s0, v253, 62
	v_readlane_b32 s1, v253, 63
	s_mov_b64 s[24:25], s[42:43]
	v_mov_b32_e32 v0, v209
	s_andn2_b64 vcc, exec, s[0:1]
	s_cbranch_vccnz .LBB0_444
	s_movk_i32 s0, 0x100
	v_ashrrev_i32_e32 v71, 2, v0
	v_cmp_gt_i32_e64 s[38:39], s0, v0
	s_movk_i32 s0, 0x200
	v_ashrrev_i32_e32 v70, 4, v0
	v_lshlrev_b32_e32 v72, 1, v71
	v_cmp_gt_i32_e64 s[42:43], s0, v0
	s_movk_i32 s0, 0x84
	v_and_b32_e32 v53, 15, v0
	v_add_u32_e32 v1, 0, v72
	s_waitcnt vmcnt(2)
	v_mul_lo_u32 v6, v70, s0
	v_add_u32_e32 v4, v1, v72
	v_bfe_u32 v5, v0, 4, 2
	v_lshlrev_b32_e32 v75, 2, v6
	v_lshlrev_b32_e32 v6, 5, v53
	s_waitcnt vmcnt(0)
	v_ashrrev_i32_e32 v8, 3, v0
	v_add3_u32 v76, 0, v75, v6
	v_lshlrev_b32_e32 v6, 9, v53
	v_readlane_b32 s4, v254, 11
	v_lshlrev_b32_e32 v8, 1, v8
	v_lshlrev_b32_e32 v9, 1, v70
	v_mad_u64_u32 v[54:55], s[0:1], v71, 60, v[4:5]
	v_and_b32_e32 v3, 3, v0
	v_add_u32_e32 v7, s4, v6
	v_and_b32_e32 v8, -16, v8
	v_and_b32_e32 v9, 6, v9
	s_movk_i32 s0, 0xffc4
	v_add3_u32 v77, v7, v8, v9
	v_mul_u32_u24_e32 v80, 0x210, v3
	v_mul_u32_u24_e32 v7, 0x220, v3
	v_mul_lo_u32 v84, v71, s0
	v_readlane_b32 s0, v254, 12
	v_lshl_add_u32 v81, v80, 2, v4
	v_lshl_add_u32 v82, v7, 1, v1
	v_and_b32_e32 v206, 12, v71
	v_lshlrev_b32_e32 v206, 1, v206
	v_bfe_u32 v207, v71, 4, 1
	v_lshl_or_b32 v206, v207, 2, v206
	v_and_b32_e32 v207, 3, v71
	v_or_b32_e32 v206, v206, v207
	v_and_b32_e32 v207, 0xffffffe0, v71
	v_or_b32_e32 v206, v206, v207
	v_lshlrev_b32_e32 v206, 1, v206
	v_sub_u32_e32 v82, v82, v72
	v_add_u32_e32 v82, v82, v206
	v_add_u32_e32 v1, s0, v6
	v_and_b32_e32 v4, -16, v71
	v_add3_u32 v85, v1, v8, v9
	v_and_b32_e32 v204, 3, v53
	v_lshlrev_b32_e32 v204, 4, v204
	v_xor_b32_e32 v77, v77, v204
	v_xor_b32_e32 v85, v85, v204
	v_bfe_u32 v204, v53, 2, 1
	v_lshlrev_b32_e32 v204, 6, v204
	v_sub_u32_e32 v180, v77, v204
	v_sub_u32_e32 v181, v85, v204
	v_add_u32_e32 v77, v77, v204
	v_add_u32_e32 v85, v85, v204
	v_lshlrev_b32_e32 v89, 4, v5
	v_lshlrev_b32_e32 v56, 3, v5
	v_lshlrev_b32_e32 v1, 2, v5
	v_ashrrev_i32_e32 v5, 31, v4
	v_lshl_add_u64 v[4:5], v[4:5], 1, s[82:83]
	v_mov_b32_e32 v57, v2
	v_lshlrev_b32_e32 v83, 6, v71
	v_lshl_add_u64 v[58:59], v[4:5], 0, v[56:57]
	v_lshlrev_b32_e32 v4, 4, v53
	v_mov_b32_e32 v5, v2
	s_movk_i32 s0, 0x10ff
	v_cmp_lt_i32_e64 s[40:41], s22, v0
	v_lshlrev_b32_e32 v73, 4, v0
	v_lshl_add_u64 v[60:61], s[82:83], 0, v[4:5]
	v_lshlrev_b32_e32 v57, 6, v53
	v_cmp_gt_u32_e64 s[48:49], v1, v53
	v_cmp_lt_u32_e64 s[50:51], v1, v53
	v_or_b32_e32 v4, 2, v1
	v_or_b32_e32 v1, 3, v1
	v_bitop3_b32 v92, v0, s0, 15 bitop3:0x6c
	v_and_b32_e32 v0, 0xfffffc00, v83
	v_cmp_gt_u32_e64 s[54:55], v1, v53
	v_lshlrev_b32_e32 v1, 10, v3
	v_or3_b32 v0, v0, v57, v89
	v_sub_u32_e32 v74, 0xff, v70
	v_lshlrev_b32_e32 v52, 3, v53
	v_add_u32_e32 v78, 16, v70
	v_sub_u32_e32 v79, 0xef, v70
	v_cmp_eq_u32_e64 s[44:45], 0, v3
	v_cmp_lt_u32_e64 s[46:47], 1, v3
	v_lshlrev_b32_e32 v55, 4, v3
	v_add_u32_e32 v86, 32, v70
	v_sub_u32_e32 v87, 0xdf, v70
	v_mul_u32_u24_e32 v88, 0x110, v53
	v_cmp_gt_u32_e64 s[52:53], v4, v53
	v_sub_u32_e32 v90, 0, v1
	v_sub_u32_e32 v91, 0, v70
	v_lshrrev_b32_e32 v204, 5, v0
	v_and_b32_e32 v204, 0x70, v204
	v_xor_b32_e32 v0, v0, v204
	v_add_u32_e32 v93, s4, v0
	s_mov_b32 s13, s2
	s_branch .LBB0_418

; #define LAS __attribute__((address_space(3)))
; #define SC_LOAD(c_) do { const bf16* rp_ = proj + (size_t)scan_row16(b, dir, (c_), st) * HIN + h * 128 + sc8 * 8; \
;         rq = *(const u32x4*)rp_; rk = *(const u32x4*)(rp_ + kcol - h * 128); rv = *(const u32x4*)(rp_ + 3072); } while (0)
; __device__ __forceinline__ void scan_phase(LAS unsigned char* lds, bf16* proj, int G, int bid) {
;     ...
;         __syncthreads();
;         {
;             const u32x4 z4 = (u32x4){0u, 0u, 0u, 0u};
;             for (int o_ = tid * 16; o_ < 8192; o_ += NTHR * 16) { *(LAS u32x4*)(lds + O_KD + o_) = z4; *(LAS u32x4*)(lds + SET + O_KD + o_) = z4; *(LAS u32x4*)(lds + O_VT + o_) = z4; *(LAS u32x4*)(lds + O_VT + 8192 + o_) = z4; *(LAS u32x4*)(lds + O_VT + 16384 + o_) = z4; }
;         }
;         if (stager) SC_LOAD(0);
;         __syncthreads();
;         if (stager) { SC_WRITE(0); SC_LOAD(1); }
;         __syncthreads();
;         SC_PREP(0);
;         if (stager) { SC_WRITE(1); SC_LOAD(2); }
;         __syncthreads();
; #pragma unroll 1
;         for (int c = 0; c < 272; ++c) {
;             LAS unsigned char* set = lds + (c & 1) * SET;
;             SC_PREP(c + 1);
;             {
;                 const LAS unsigned char* qeb = set + O_QE + fr * QST; const LAS unsigned char* keb = set + O_KE + fr * QST;
;                 bf16x8 kaf[4], qbf[4];
; #pragma unroll
;                 for (int i = 0; i < 4; ++i) { kaf[i] = *(const LAS bf16x8*)(keb + (32 * i + fq * 8) * 2); qbf[i] = *(const LAS bf16x8*)(qeb + (32 * i + fq * 8) * 2); }
;                 u32x2 qlo[4], qhi[4];
; #pragma unroll
;                 for (int i = 0; i < 4; ++i) { qlo[i] = *(const LAS u32x2*)(qeb + (32 * i + fq * 4) * 2); qhi[i] = *(const LAS u32x2*)(qeb + (32 * i + 16 + fq * 4) * 2); }
;                 const bf16x8 vf = *(const LAS bf16x8*)(lds + O_VT + (c % 3) * 8192 + (wave * 16 + fr) * 64 + fq * 16);
;                 f32x4 pt = (f32x4){0.f, 0.f, 0.f, 0.f};
;                 __builtin_amdgcn_s_setprio(1);
; #pragma unroll
;                 for (int i = 0; i < 4; ++i) pt = __builtin_amdgcn_mfma_f32_16x16x32_bf16(kaf[i], qbf[i], pt, 0, 0, 0);
.LBB0_433:
	s_add_i32 s7, s6, 1
	s_bitcmp1_b32 s7, 0
	s_cselect_b32 s0, 0x8600, 0
	s_add_i32 s0, s0, 0
	v_lshl_add_u32 v1, v80, 2, s0
	v_lshl_add_u32 v0, v71, 2, v1
	ds_read2_b32 v[48:49], v0 offset1:132
	v_add_u32_e32 v3, 0x2000, v0
	ds_read2_b32 v[50:51], v3 offset0:64 offset1:196
	v_add_u32_e32 v3, 0x400, v0
	ds_read2_b32 v[98:99], v3 offset0:8 offset1:140
	v_add_u32_e32 v0, 0x2400, v0
	ds_read2_b32 v[100:101], v0 offset0:72 offset1:204
	s_waitcnt lgkmcnt(3)
	v_sub_f32_e32 v0, 1.0, v48
	v_max_f32_e32 v3, 0x3bdb8bac, v0
	v_sub_f32_e32 v0, 1.0, v49
	v_max_f32_e32 v0, 0x3bdb8bac, v0
	v_mul_f32_e32 v65, v3, v0
	s_waitcnt lgkmcnt(1)
	v_sub_f32_e32 v0, 1.0, v98
	v_max_f32_e32 v0, 0x3bdb8bac, v0
	v_mul_f32_e32 v104, v65, v0
	v_sub_f32_e32 v0, 1.0, v99
	v_max_f32_e32 v0, 0x3bdb8bac, v0
	v_mul_f32_e32 v105, v104, v0
	v_add3_u32 v1, v1, v90, v206
	s_nop 0
	v_mul_f32_dpp v0, v105, v105 quad_perm:[0,0,1,2] row_mask:0xf bank_mask:0xf bound_ctrl:1
	v_cndmask_b32_e64 v0, v0, v105, s[44:45]
	s_nop 1
	v_mul_f32_dpp v102, v0, v0 quad_perm:[0,0,0,1] row_mask:0xf bank_mask:0xf bound_ctrl:1
	v_cndmask_b32_e64 v102, v0, v102, s[46:47]
	v_mov_b32_e32 v0, 0
	s_nop 1
	v_mov_b32_dpp v0, v102 quad_perm:[0,0,1,2] row_mask:0xf bank_mask:0xf
	v_cndmask_b32_e64 v106, v0, 1.0, s[44:45]
	v_mov_b32_e32 v0, 0
	v_mul_f32_e32 v3, v3, v106
	s_nop 0
	v_mov_b32_dpp v0, v102 quad_perm:[3,3,3,3] row_mask:0xf bank_mask:0xf
	v_rcp_f32_e32 v102, v3
	v_mul_f32_e32 v3, v50, v3
	v_cvt_pk_bf16_f32 v3, v3, s0
	ds_write_b16 v1, v3 offset:16896
	v_mul_f32_e32 v3, v65, v106
	v_rcp_f32_e32 v103, v3
	v_mul_f32_e32 v3, v51, v3
	v_cvt_pk_bf16_f32 v3, v3, s0
	ds_write_b16 v1, v3 offset:17168
	v_mul_f32_e32 v3, v104, v106
	v_rcp_f32_e32 v50, v3
	s_waitcnt lgkmcnt(2)
	v_mul_f32_e32 v3, v100, v3
	v_cvt_pk_bf16_f32 v3, v3, s0
	ds_write_b16 v1, v3 offset:17440
	v_mul_f32_e32 v3, v105, v106
	v_rcp_f32_e32 v51, v3
	v_mul_f32_e32 v3, v101, v3
	v_cvt_pk_bf16_f32 v3, v3, s0
	v_pk_mul_f32 v[48:49], v[48:49], v[102:103]
	ds_write_b16 v1, v3 offset:17712
	v_cvt_pk_bf16_f32 v3, v48, s0
	ds_write_b16 v1, v3 offset:21248
	v_cvt_pk_bf16_f32 v3, v49, s0
	v_pk_mul_f32 v[50:51], v[98:99], v[50:51]
	ds_write_b16 v1, v3 offset:21520
	v_cvt_pk_bf16_f32 v3, v50, s0
	ds_write_b16 v1, v3 offset:21792
	v_cvt_pk_bf16_f32 v3, v51, s0
	v_pk_mul_f32 v[100:101], v[48:49], v[0:1] op_sel_hi:[1,0]
	v_pk_mul_f32 v[98:99], v[50:51], v[0:1] op_sel_hi:[1,0]
	ds_write_b16 v1, v3 offset:22064
	v_add_u32_e32 v1, s0, v83
	v_cvt_pk_bf16_f32 v48, v100, v101
	v_cvt_pk_bf16_f32 v49, v98, v99
	v_add_u32_e32 v3, v1, v55
	ds_write_b64 v3, v[48:49] offset:25600
	s_and_saveexec_b64 s[0:1], s[44:45]
	v_add_u32_e32 v1, v1, v84
	ds_write_b32 v1, v0 offset:33792
	s_or_b64 exec, exec, s[0:1]
	s_mul_hi_u32 s0, s6, 0xaaaaaaab
	s_lshr_b32 s0, s0, 1
	s_bitcmp1_b32 s6, 0
	s_cselect_b32 s1, 0x8600, 0
	s_add_i32 s14, s1, 0
	v_add_u32_e32 v0, s14, v88
	v_add_u32_e32 v1, v0, v89
	ds_read_b128 v[48:51], v1 offset:21248
	ds_read_b128 v[98:101], v1 offset:21312
	ds_read_b128 v[126:129], v1 offset:16896
	ds_read_b128 v[130:133], v1 offset:16960
	ds_read_b128 v[110:113], v1 offset:21376
	ds_read_b128 v[114:117], v1 offset:21440
	ds_read_b128 v[134:137], v1 offset:17024
	ds_read_b128 v[138:141], v1 offset:17088
	s_mulk_i32 s0, 0xa000
	v_add_u32_e32 v0, s0, v95
	ds_read_b128 v[142:145], v0
	s_setprio 1
	s_waitcnt lgkmcnt(6)
	v_mfma_f32_16x16x32_bf16 v[48:51], v[48:51], v[126:129], 0
	v_add_u32_e32 v0, s14, v89
	v_add_u32_e32 v1, v0, v57
	v_cvt_pk_bf16_f32 v146, v44, v45
	s_waitcnt lgkmcnt(5)
	v_mfma_f32_16x16x32_bf16 v[48:51], v[98:101], v[130:133], v[48:51]
	ds_read_b128 v[98:101], v1 offset:25600
	ds_read_b128 v[104:107], v0 offset:33792
	v_cvt_pk_bf16_f32 v147, v46, v47
	v_cvt_pk_bf16_f32 v148, v16, v17
	s_waitcnt lgkmcnt(4)
; #define LAS __attribute__((address_space(3)))
; __device__ __forceinline__ void scan_phase(LAS unsigned char* lds, bf16* proj, int G, int bid) {
;     ...
;                 for (int i = 0; i < 4; ++i) { qlo[i] = *(const LAS u32x2*)(qeb + (32 * i + fq * 4) * 2); qhi[i] = *(const LAS u32x2*)(qeb + (32 * i + 16 + fq * 4) * 2); }
;                 const bf16x8 vf = *(const LAS bf16x8*)(lds + O_VT + (c % 3) * 8192 + (wave * 16 + fr) * 64 + fq * 16);
;                 f32x4 pt = (f32x4){0.f, 0.f, 0.f, 0.f};
;                 __builtin_amdgcn_s_setprio(1);
; #pragma unroll
;                 for (int i = 0; i < 4; ++i) pt = __builtin_amdgcn_mfma_f32_16x16x32_bf16(kaf[i], qbf[i], pt, 0, 0, 0);
;                 f32x4 oacc = (f32x4){0.f, 0.f, 0.f, 0.f};
; #pragma unroll
;                 for (int i = 0; i < 4; ++i) {
;                     u32x4 sw; sw.x = cvt_pk_bf16(S[2 * i][0], S[2 * i][1]); sw.y = cvt_pk_bf16(S[2 * i][2], S[2 * i][3]); sw.z = cvt_pk_bf16(S[2 * i + 1][0], S[2 * i + 1][1]); sw.w = cvt_pk_bf16(S[2 * i + 1][2], S[2 * i + 1][3]);
;                     u32x4 qw; qw.x = qlo[i][0]; qw.y = qlo[i][1]; qw.z = qhi[i][0]; qw.w = qhi[i][1];
;                     oacc = __builtin_amdgcn_mfma_f32_16x16x32_bf16(__builtin_bit_cast(bf16x8, sw), __builtin_bit_cast(bf16x8, qw), oacc, 0, 0, 0);
;                 }
;                 const LAS float* dv = (const LAS float*)(set + O_DV);
; #pragma unroll
;                 for (int kt = 0; kt < 8; ++kt) {
;                     const f32x4 d4 = *(const LAS f32x4*)(dv + kt * 16 + fq * 4);
;                     const bf16x8 ka = *(const LAS bf16x8*)(set + O_KD + (kt * 16 + fr) * 64 + fq * 16);
;                     S[kt] = __builtin_amdgcn_mfma_f32_16x16x32_bf16(ka, vf, S[kt] * d4, 0, 0, 0);
;                 }
; #pragma unroll
;                 for (int j = 0; j < 4; ++j) pt[j] = (fq * 4 + j <= fr) ? pt[j] : 0.f;
;                 u32x4 pw; pw.x = cvt_pk_bf16(pt[0], pt[1]); pw.y = cvt_pk_bf16(pt[2], pt[3]); pw.z = 0u; pw.w = 0u;
;                 oacc = __builtin_amdgcn_mfma_f32_16x16x32_bf16(vf, __builtin_bit_cast(bf16x8, pw), oacc, 0, 0, 0);
	v_mfma_f32_16x16x32_bf16 v[48:51], v[110:113], v[134:137], v[48:51]
	ds_read_b128 v[108:111], v0 offset:33856
	ds_read_b128 v[118:121], v1 offset:26624
	s_waitcnt lgkmcnt(2)
	v_pk_mul_f32 v[46:47], v[46:47], v[106:107]
	v_pk_mul_f32 v[44:45], v[44:45], v[104:105]
	ds_read_b128 v[158:161], v1 offset:32768
	s_waitcnt lgkmcnt(2)
	v_pk_mul_f32 v[16:17], v[16:17], v[108:109]
	v_mfma_f32_16x16x32_bf16 v[44:47], v[98:101], v[142:145], v[44:47]
	ds_read_b128 v[98:101], v1 offset:27648
	ds_read_b128 v[106:109], v0 offset:33920
	v_cvt_pk_bf16_f32 v149, v18, v19
	v_cvt_pk_bf16_f32 v150, v20, v21
	v_cvt_pk_bf16_f32 v151, v22, v23
	v_pk_mul_f32 v[18:19], v[18:19], v[110:111]
	s_waitcnt lgkmcnt(0)
	v_pk_mul_f32 v[22:23], v[22:23], v[108:109]
	v_pk_mul_f32 v[20:21], v[20:21], v[106:107]
	v_mfma_f32_16x16x32_bf16 v[16:19], v[118:121], v[142:145], v[16:19]
	ds_read_b128 v[110:113], v0 offset:33984
	ds_read_b128 v[118:121], v1 offset:28672
	v_cvt_pk_bf16_f32 v152, v24, v25
	v_cvt_pk_bf16_f32 v153, v26, v27
	v_mfma_f32_16x16x32_bf16 v[20:23], v[98:101], v[142:145], v[20:23]
	ds_read_b128 v[98:101], v1 offset:29696
	ds_read_b128 v[106:109], v0 offset:34048
	s_waitcnt lgkmcnt(3)
	v_pk_mul_f32 v[26:27], v[26:27], v[112:113]
	v_pk_mul_f32 v[24:25], v[24:25], v[110:111]
	v_cvt_pk_bf16_f32 v154, v28, v29
	v_cvt_pk_bf16_f32 v155, v30, v31
	s_waitcnt lgkmcnt(2)
	v_mfma_f32_16x16x32_bf16 v[24:27], v[118:121], v[142:145], v[24:27]
	ds_read_b128 v[110:113], v1 offset:30720
	ds_read_b128 v[118:121], v0 offset:34112
	s_waitcnt lgkmcnt(2)
	v_pk_mul_f32 v[30:31], v[30:31], v[108:109]
	v_pk_mul_f32 v[28:29], v[28:29], v[106:107]
	v_cvt_pk_bf16_f32 v156, v32, v33
	v_cvt_pk_bf16_f32 v157, v34, v35
	v_mfma_f32_16x16x32_bf16 v[28:31], v[98:101], v[142:145], v[28:31]
	ds_read_b128 v[98:101], v0 offset:34176
	s_waitcnt lgkmcnt(1)
	v_pk_mul_f32 v[34:35], v[34:35], v[120:121]
	v_pk_mul_f32 v[32:33], v[32:33], v[118:119]
	v_cvt_pk_bf16_f32 v102, v36, v37
	v_cvt_pk_bf16_f32 v103, v38, v39
	v_mfma_f32_16x16x32_bf16 v[32:35], v[110:113], v[142:145], v[32:35]
	ds_read_b128 v[110:113], v0 offset:34240
	s_waitcnt lgkmcnt(1)
	v_pk_mul_f32 v[38:39], v[38:39], v[100:101]
	v_pk_mul_f32 v[36:37], v[36:37], v[98:99]
	v_mfma_f32_16x16x32_bf16 v[98:101], v[146:149], v[126:129], 0
	v_cvt_pk_bf16_f32 v104, v40, v41
	ds_read_b128 v[106:109], v1 offset:31744
	v_cvt_pk_bf16_f32 v105, v42, v43
	v_mfma_f32_16x16x32_bf16 v[98:101], v[150:153], v[130:133], v[98:101]
	s_waitcnt lgkmcnt(1)
	v_pk_mul_f32 v[42:43], v[42:43], v[112:113]
	v_pk_mul_f32 v[40:41], v[40:41], v[110:111]
	v_mfma_f32_16x16x32_bf16 v[48:51], v[114:117], v[138:141], v[48:51]
	v_mfma_f32_16x16x32_bf16 v[98:101], v[154:157], v[134:137], v[98:101]
	v_mfma_f32_16x16x32_bf16 v[98:101], v[102:105], v[138:141], v[98:101]
	s_nop 5
	v_cvt_pk_bf16_f32 v0, v48, s0
	v_cvt_pk_bf16_f32 v1, v49, s0
	v_cndmask_b32_e64 v0, v0, 0, s[48:49]
	v_cndmask_b32_e64 v1, 0, v1, s[50:51]
	v_perm_b32 v0, v1, v0, s11
	v_cvt_pk_bf16_f32 v1, v50, s0
	v_cvt_pk_bf16_f32 v3, v51, s0
	v_cndmask_b32_e64 v1, v1, 0, s[52:53]
	v_cndmask_b32_e64 v3, v3, 0, s[54:55]
	v_perm_b32 v1, v3, v1, s11
	v_mov_b32_e32 v3, v2
	s_waitcnt lgkmcnt(0)
	v_mfma_f32_16x16x32_bf16 v[36:39], v[106:109], v[142:145], v[36:39]
	v_mfma_f32_16x16x32_bf16 v[40:43], v[158:161], v[142:145], v[40:43]
	v_mfma_f32_16x16x32_bf16 v[48:51], v[142:145], v[0:3], v[98:101]
	s_setprio 0
	s_mov_b64 s[0:1], -1
	s_cmp_gt_u32 s6, 15
	v_add_u32_e32 v1, s4, v53
	s_cbranch_scc0 .LBB0_437
	v_add_u32_e32 v0, 0xffffff00, v1
	v_cndmask_b32_e64 v0, v96, v0, s[56:57]
	v_add_u32_e32 v0, s5, v0
	s_mov_b64 s[0:1], 0
